# GQA loop first half: p1 scaling via 8 v_pk_fma_f32 into spare VGPRs (consumers renamed); on top of v37
# speedup vs baseline: 1.0121x; 1.0009x over previous
; template <int DK>
; __device__ __forceinline__ void partialSM(f32x16& p0, f32x16& p1, float& m_reg, float& mn, float& alpha) {
;     ...
;   float mnC = -mn * C;
; #pragma unroll
;   for (int r = 0; r < 16; ++r) p0[r] = fmaf(p0[r], C, mnC);
; #pragma unroll
;   for (int r = 0; r < 16; ++r) p1[r] = fmaf(p1[r], C, mnC);
; #pragma unroll
;   for (int r = 0; r < 16; ++r) p0[r] = __builtin_amdgcn_exp2f(p0[r]);
; }
; __device__ __forceinline__ void finishSM(f32x16& p0, f32x16& p1, float alpha, float& l_reg, bf16x8& pa0, bf16x8& pa1, bf16x8& pa2, bf16x8& pa3) {
; #pragma unroll
;   for (int r = 0; r < 16; ++r) p1[r] = __builtin_amdgcn_exp2f(p1[r]);
;   float ps = 0;
; #pragma unroll
;   for (int r = 0; r < 16; ++r) ps += p0[r];
; #pragma unroll
;   for (int r = 0; r < 16; ++r) ps += p1[r];
;   { auto rr = __builtin_amdgcn_permlane32_swap(__float_as_uint(ps), __float_as_uint(ps), false, false);
;     ps = __uint_as_float(rr[0]) + __uint_as_float(rr[1]); }
;   l_reg = l_reg * alpha + ps;
;     ...
;   PK4(p0, 0, pa0); PK4(p0, 8, pa1); PK4(p1, 0, pa2); PK4(p1, 8, pa3);
;     ...
; }
; template <int DK, int NPARK>
; __device__ __forceinline__ void qkt(f32x16& p0, f32x16& p1, const char* Ks, const bf16x8* qr, const char* qpark, int r32, int hi) {
;   p0 = f32x16{}; p1 = f32x16{};
; #pragma unroll
;   for (int d0 = 0; d0 < DK / 16; ++d0) { const int cb = (d0 * 16 + hi * 8) * 2;
;     bf16x8 b0 = *reinterpret_cast<const bf16x8*>(Ks + kswz<DK>(r32, cb));
;     bf16x8 b1 = *reinterpret_cast<const bf16x8*>(Ks + kswz<DK>(32 + r32, cb));
;     bf16x8 q;
;     if constexpr (NPARK > 0) { if (d0 >= DK / 16 - NPARK) q = *reinterpret_cast<const bf16x8*>(qpark + (d0 - (DK / 16 - NPARK)) * 1024); else q = qr[d0]; } else q = qr[d0];
;     p0 = __builtin_amdgcn_mfma_f32_32x32x16_bf16(b0, q, p0, 0, 0, 0);
;     p1 = __builtin_amdgcn_mfma_f32_32x32x16_bf16(b1, q, p1, 0, 0, 0); }
.LBB0_928:
	v_cndmask_b32_e64 v174, v144, v174, s[8:9]
	v_mul_f32_e32 v144, 0xbe0293ee, v174
	v_pk_fma_f32 v[80:81], v[80:81], s[76:77], v[144:145] op_sel_hi:[1,0,0]
	v_pk_fma_f32 v[82:83], v[82:83], s[76:77], v[144:145] op_sel_hi:[1,0,0]
	v_pk_fma_f32 v[84:85], v[84:85], s[76:77], v[144:145] op_sel_hi:[1,0,0]
	v_pk_fma_f32 v[86:87], v[86:87], s[76:77], v[144:145] op_sel_hi:[1,0,0]
	v_pk_fma_f32 v[88:89], v[88:89], s[76:77], v[144:145] op_sel_hi:[1,0,0]
	v_pk_fma_f32 v[90:91], v[90:91], s[76:77], v[144:145] op_sel_hi:[1,0,0]
	v_pk_fma_f32 v[92:93], v[92:93], s[76:77], v[144:145] op_sel_hi:[1,0,0]
	v_pk_fma_f32 v[94:95], v[94:95], s[76:77], v[144:145] op_sel_hi:[1,0,0]
	v_pk_fma_f32 v[214:215], v[64:65], s[76:77], v[144:145] op_sel_hi:[1,0,0]
	v_pk_fma_f32 v[216:217], v[66:67], s[76:77], v[144:145] op_sel_hi:[1,0,0]
	v_pk_fma_f32 v[218:219], v[68:69], s[76:77], v[144:145] op_sel_hi:[1,0,0]
	v_pk_fma_f32 v[220:221], v[70:71], s[76:77], v[144:145] op_sel_hi:[1,0,0]
	v_pk_fma_f32 v[222:223], v[72:73], s[76:77], v[144:145] op_sel_hi:[1,0,0]
	v_pk_fma_f32 v[224:225], v[74:75], s[76:77], v[144:145] op_sel_hi:[1,0,0]
	v_pk_fma_f32 v[226:227], v[76:77], s[76:77], v[144:145] op_sel_hi:[1,0,0]
	v_pk_fma_f32 v[228:229], v[78:79], s[76:77], v[144:145] op_sel_hi:[1,0,0]
	v_exp_f32_e32 v141, v80
	v_exp_f32_e32 v143, v81
	v_exp_f32_e32 v139, v82
	v_exp_f32_e32 v142, v83
	v_exp_f32_e32 v138, v84
	v_exp_f32_e32 v140, v85
	v_exp_f32_e32 v136, v86
	v_exp_f32_e32 v137, v87
	v_exp_f32_e32 v133, v88
	v_exp_f32_e32 v135, v89
	v_exp_f32_e32 v132, v90
	v_exp_f32_e32 v134, v91
	v_exp_f32_e32 v129, v92
	v_exp_f32_e32 v131, v93
	v_exp_f32_e32 v128, v94
	v_exp_f32_e32 v130, v95
	s_waitcnt lgkmcnt(0)
	s_barrier
	ds_read_b128 v[64:67], v161 offset:32768
	ds_read_b128 v[68:71], v161 offset:40960
	ds_read_b128 v[194:197], v170 offset:32768
	ds_read_b128 v[198:201], v170 offset:40960
	v_exp_f32_e32 v203, v229
	s_waitcnt lgkmcnt(3)
	v_mfma_f32_32x32x16_bf16 v[80:95], v[64:67], v[112:115], 0
	v_add_f32_e32 v144, v143, v141
	v_add_f32_e32 v144, v139, v144
	v_add_f32_e32 v144, v142, v144
	v_add_f32_e32 v144, v138, v144
	v_add_f32_e32 v144, v140, v144
	v_add_f32_e32 v144, v136, v144
	v_add_f32_e32 v144, v137, v144
	s_waitcnt lgkmcnt(2)
	v_mfma_f32_32x32x16_bf16 v[64:79], v[68:71], v[112:115], 0
	v_add_f32_e32 v144, v133, v144
	v_add_f32_e32 v144, v135, v144
	v_add_f32_e32 v144, v132, v144
	v_add_f32_e32 v144, v134, v144
	v_exp_f32_e32 v191, v214
	v_add_f32_e32 v144, v129, v144
	v_exp_f32_e32 v185, v215
	s_waitcnt lgkmcnt(1)
	v_mfma_f32_32x32x16_bf16 v[80:95], v[194:197], v[108:111], v[80:95]
	v_add_f32_e32 v144, v131, v144
	v_add_f32_e32 v144, v128, v144
	v_add_f32_e32 v144, v130, v144
	v_add_f32_e32 v144, v191, v144
	v_add_f32_e32 v144, v185, v144
	v_exp_f32_e32 v179, v221
	v_exp_f32_e32 v180, v222
	s_waitcnt lgkmcnt(0)
	v_mfma_f32_32x32x16_bf16 v[64:79], v[198:201], v[108:111], v[64:79]
	ds_read_b128 v[194:197], v169 offset:32768
	ds_read_b128 v[198:201], v169 offset:40960
	v_exp_f32_e32 v181, v223
	v_exp_f32_e32 v182, v224
	v_exp_f32_e32 v202, v227
	v_exp_f32_e32 v190, v228
	s_waitcnt lgkmcnt(1)
	v_mfma_f32_32x32x16_bf16 v[80:95], v[194:197], v[120:123], v[80:95]
	s_waitcnt lgkmcnt(0)
	v_mfma_f32_32x32x16_bf16 v[64:79], v[198:201], v[120:123], v[64:79]
	ds_read_b128 v[194:197], v168 offset:32768
	ds_read_b128 v[198:201], v168 offset:40960
	s_waitcnt lgkmcnt(1)
	v_mfma_f32_32x32x16_bf16 v[80:95], v[194:197], v[124:127], v[80:95]
	s_waitcnt lgkmcnt(0)
	v_mfma_f32_32x32x16_bf16 v[64:79], v[198:201], v[124:127], v[64:79]
	ds_read_b128 v[194:197], v167 offset:32768
	ds_read_b128 v[198:201], v167 offset:40960
	s_waitcnt lgkmcnt(1)
	v_mfma_f32_32x32x16_bf16 v[80:95], v[194:197], v[116:119], v[80:95]
	s_waitcnt lgkmcnt(0)
	v_mfma_f32_32x32x16_bf16 v[64:79], v[198:201], v[116:119], v[64:79]
	ds_read_b128 v[194:197], v166 offset:32768
	ds_read_b128 v[198:201], v166 offset:40960
	s_waitcnt lgkmcnt(1)
	v_mfma_f32_32x32x16_bf16 v[80:95], v[194:197], v[104:107], v[80:95]
	s_waitcnt lgkmcnt(0)
	v_mfma_f32_32x32x16_bf16 v[64:79], v[198:201], v[104:107], v[64:79]
	ds_read_b128 v[194:197], v172 offset:32768
	ds_read_b128 v[198:201], v172 offset:40960
	s_waitcnt lgkmcnt(1)
	v_mfma_f32_32x32x16_bf16 v[80:95], v[194:197], v[100:103], v[80:95]
	s_waitcnt lgkmcnt(0)
	v_mfma_f32_32x32x16_bf16 v[64:79], v[198:201], v[100:103], v[64:79]
	ds_read_b128 v[194:197], v171 offset:32768
	ds_read_b128 v[198:201], v171 offset:40960
	s_waitcnt lgkmcnt(1)
	v_mfma_f32_32x32x16_bf16 v[80:95], v[194:197], v[96:99], v[80:95]
	v_exp_f32_e32 v195, v216
	v_exp_f32_e32 v196, v217
	v_exp_f32_e32 v197, v218
	v_add_f32_e32 v144, v195, v144
	v_add_f32_e32 v144, v196, v144
	v_add_f32_e32 v144, v197, v144
	s_waitcnt lgkmcnt(0)
; __device__ __forceinline__ void finishSM(f32x16& p0, f32x16& p1, float alpha, float& l_reg, bf16x8& pa0, bf16x8& pa1, bf16x8& pa2, bf16x8& pa3) {
; #pragma unroll
;   for (int r = 0; r < 16; ++r) p1[r] = __builtin_amdgcn_exp2f(p1[r]);
;   float ps = 0;
; #pragma unroll
;   for (int r = 0; r < 16; ++r) ps += p0[r];
; #pragma unroll
;   for (int r = 0; r < 16; ++r) ps += p1[r];
;   { auto rr = __builtin_amdgcn_permlane32_swap(__float_as_uint(ps), __float_as_uint(ps), false, false);
;     ps = __uint_as_float(rr[0]) + __uint_as_float(rr[1]); }
;   l_reg = l_reg * alpha + ps;
;     ...
;   PK4(p0, 0, pa0); PK4(p0, 8, pa1); PK4(p1, 0, pa2); PK4(p1, 8, pa3);
;     ...
; }
; template <int DK, int NPARK>
; __device__ __forceinline__ void qkt(f32x16& p0, f32x16& p1, const char* Ks, const bf16x8* qr, const char* qpark, int r32, int hi) {
;   p0 = f32x16{}; p1 = f32x16{};
; #pragma unroll
;   for (int d0 = 0; d0 < DK / 16; ++d0) { const int cb = (d0 * 16 + hi * 8) * 2;
;     bf16x8 b0 = *reinterpret_cast<const bf16x8*>(Ks + kswz<DK>(r32, cb));
;     bf16x8 b1 = *reinterpret_cast<const bf16x8*>(Ks + kswz<DK>(32 + r32, cb));
;     bf16x8 q;
;     if constexpr (NPARK > 0) { if (d0 >= DK / 16 - NPARK) q = *reinterpret_cast<const bf16x8*>(qpark + (d0 - (DK / 16 - NPARK)) * 1024); else q = qr[d0]; } else q = qr[d0];
;     p0 = __builtin_amdgcn_mfma_f32_32x32x16_bf16(b0, q, p0, 0, 0, 0);
;     p1 = __builtin_amdgcn_mfma_f32_32x32x16_bf16(b1, q, p1, 0, 0, 0); }
; }
; __device__ __forceinline__ int v_st(int k, int c) { const int kk = (k & ~0xC) | ((k & 4) << 1) | ((k & 8) >> 1); return ((kk >> 3) * 4 + (c >> 5)) * 512 + ((kk & 7) * 32 + (c & 31)) * 2; }
; __device__ __forceinline__ int v_rd_base(int lane) { return ((lane & 3) << 3) | (((lane >> 2) & 3) << 6) | (((lane >> 4) & 1) << 5) | (((lane >> 5) & 1) << 8); }
; template <int OFF> __device__ __forceinline__ s16x4 tr_read(int vb) {
;   s16x4 r; asm volatile("ds_read_b64_tr_b16 %0, %1 offset:%2" : "=&v"(r) : "v"(vb), "i"(OFF) : "memory"); return r;
; }
; template <int D0> __device__ __forceinline__ void pv_one(f32x16& od, int vb, bf16x8 pa0, bf16x8 pa1, bf16x8 pa2, bf16x8 pa3) {
;   const s16x4 l0 = tr_read<v_rd_off(D0, 0, 0)>(vb), h0 = tr_read<v_rd_off(D0, 0, 1)>(vb), l1 = tr_read<v_rd_off(D0, 1, 0)>(vb), h1 = tr_read<v_rd_off(D0, 1, 1)>(vb);
	v_mfma_f32_32x32x16_bf16 v[64:79], v[198:201], v[96:99], v[64:79]
	v_exp_f32_e32 v198, v219
	v_exp_f32_e32 v199, v220
	v_exp_f32_e32 v200, v225
	v_exp_f32_e32 v201, v226
	v_add_f32_e32 v144, v198, v144
	v_add_f32_e32 v144, v199, v144
	v_add_f32_e32 v144, v179, v144
	v_add_f32_e32 v144, v180, v144
	v_add_f32_e32 v144, v181, v144
	v_add_f32_e32 v144, v182, v144
	v_add_f32_e32 v144, v200, v144
	v_add_f32_e32 v144, v201, v144
	v_add_f32_e32 v144, v202, v144
	v_add_f32_e32 v144, v190, v144
	v_add_f32_e32 v183, v203, v144
	v_mov_b32_e32 v184, v183
	v_cvt_pk_bf16_f32 v144, v141, v143
	v_cvt_pk_bf16_f32 v145, v139, v142
	v_cvt_pk_bf16_f32 v146, v138, v140
	v_cvt_pk_bf16_f32 v147, v136, v137
	s_nop 1
	v_permlane32_swap_b32_e32 v183, v184
	v_permlane32_swap_b32_e32 v144, v146
	v_permlane32_swap_b32_e32 v145, v147
	v_cvt_pk_bf16_f32 v186, v133, v135
	v_cvt_pk_bf16_f32 v187, v132, v134
	v_cvt_pk_bf16_f32 v188, v129, v131
	v_cvt_pk_bf16_f32 v189, v128, v130
	v_cvt_pk_bf16_f32 v194, v191, v185
	v_cvt_pk_bf16_f32 v195, v195, v196
	v_cvt_pk_bf16_f32 v196, v197, v198
	v_cvt_pk_bf16_f32 v197, v199, v179
	v_cvt_pk_bf16_f32 v198, v180, v181
	v_cvt_pk_bf16_f32 v199, v182, v200
	v_cvt_pk_bf16_f32 v200, v201, v202
	v_cvt_pk_bf16_f32 v201, v190, v203
	s_nop 0
	v_permlane32_swap_b32_e32 v186, v188
	v_permlane32_swap_b32_e32 v187, v189
	v_permlane32_swap_b32_e32 v194, v196
	v_permlane32_swap_b32_e32 v195, v197
	v_permlane32_swap_b32_e32 v198, v200
	v_permlane32_swap_b32_e32 v199, v201
	s_add_u32 s46, s10, s61
	s_addc_u32 s47, s11, 0
	s_add_u32 s48, s10, s64
	s_addc_u32 s49, s11, 0
	global_load_dwordx4 v[128:131], v192, s[46:47]
	global_load_dwordx4 v[132:135], v152, s[46:47]
	global_load_dwordx4 v[136:139], v192, s[48:49]
	global_load_dwordx4 v[140:143], v152, s[48:49]
	ds_read_b64_tr_b16 v[154:155], v159 offset:0
	ds_read_b64_tr_b16 v[156:157], v159 offset:0x800
	ds_read_b64_tr_b16 v[202:203], v159 offset:0x1000
	ds_read_b64_tr_b16 v[204:205], v159 offset:0x1800
	ds_read_b64_tr_b16 v[206:207], v159 offset:0x2000
	ds_read_b64_tr_b16 v[208:209], v159 offset:0x2800
	ds_read_b64_tr_b16 v[210:211], v159 offset:0x3000
	ds_read_b64_tr_b16 v[212:213], v159 offset:0x3800
	s_waitcnt lgkmcnt(0)
	v_mfma_f32_32x32x16_bf16 v[0:15], v[144:147], v[154:157], v[0:15]
	ds_read_b64_tr_b16 v[154:155], v159 offset:0x200
	ds_read_b64_tr_b16 v[156:157], v159 offset:0xa00
	v_mfma_f32_32x32x16_bf16 v[0:15], v[186:189], v[202:205], v[0:15]
	ds_read_b64_tr_b16 v[202:203], v159 offset:0x1200
	ds_read_b64_tr_b16 v[204:205], v159 offset:0x1a00
	v_mfma_f32_32x32x16_bf16 v[0:15], v[194:197], v[206:209], v[0:15]
	ds_read_b64_tr_b16 v[206:207], v159 offset:0x2200
	ds_read_b64_tr_b16 v[208:209], v159 offset:0x2a00
	v_mfma_f32_32x32x16_bf16 v[0:15], v[198:201], v[210:213], v[0:15]
	ds_read_b64_tr_b16 v[210:211], v159 offset:0x3200
	ds_read_b64_tr_b16 v[212:213], v159 offset:0x3a00
	s_waitcnt lgkmcnt(0)
	v_mfma_f32_32x32x16_bf16 v[48:63], v[144:147], v[154:157], v[48:63]
	ds_read_b64_tr_b16 v[154:155], v159 offset:0x400
	ds_read_b64_tr_b16 v[156:157], v159 offset:0xc00
	v_mfma_f32_32x32x16_bf16 v[48:63], v[186:189], v[202:205], v[48:63]
	ds_read_b64_tr_b16 v[202:203], v159 offset:0x1400
	ds_read_b64_tr_b16 v[204:205], v159 offset:0x1c00
	v_mfma_f32_32x32x16_bf16 v[48:63], v[194:197], v[206:209], v[48:63]
	ds_read_b64_tr_b16 v[206:207], v159 offset:0x2400
	ds_read_b64_tr_b16 v[208:209], v159 offset:0x2c00
	v_mfma_f32_32x32x16_bf16 v[48:63], v[198:201], v[210:213], v[48:63]
	ds_read_b64_tr_b16 v[210:211], v159 offset:0x3400
	ds_read_b64_tr_b16 v[212:213], v159 offset:0x3c00
	s_waitcnt lgkmcnt(0)
	v_mfma_f32_32x32x16_bf16 v[32:47], v[144:147], v[154:157], v[32:47]
	ds_read_b64_tr_b16 v[154:155], v159 offset:0x600
	ds_read_b64_tr_b16 v[156:157], v159 offset:0xe00
	v_mfma_f32_32x32x16_bf16 v[32:47], v[186:189], v[202:205], v[32:47]
	ds_read_b64_tr_b16 v[202:203], v159 offset:0x1600
	ds_read_b64_tr_b16 v[204:205], v159 offset:0x1e00
	v_mfma_f32_32x32x16_bf16 v[32:47], v[194:197], v[206:209], v[32:47]
	ds_read_b64_tr_b16 v[206:207], v159 offset:0x2600
	ds_read_b64_tr_b16 v[208:209], v159 offset:0x2e00
	v_mfma_f32_32x32x16_bf16 v[32:47], v[198:201], v[210:213], v[32:47]
	ds_read_b64_tr_b16 v[210:211], v159 offset:0x3600
	ds_read_b64_tr_b16 v[212:213], v159 offset:0x3e00
	s_waitcnt lgkmcnt(0)
	v_mfma_f32_32x32x16_bf16 v[16:31], v[144:147], v[154:157], v[16:31]
	v_max_f32_e32 v144, v80, v81
	v_max3_f32 v144, v144, v82, v83
	v_max3_f32 v144, v144, v84, v85
	v_max3_f32 v144, v144, v86, v87
	v_max3_f32 v144, v144, v88, v89
	v_max3_f32 v144, v144, v90, v91
	v_max3_f32 v144, v144, v92, v93
	v_mfma_f32_32x32x16_bf16 v[16:31], v[186:189], v[202:205], v[16:31]
	v_max3_f32 v144, v144, v94, v95
	v_max3_f32 v144, v144, v64, v65
	v_max3_f32 v144, v144, v66, v67
	v_max3_f32 v144, v144, v68, v69
	v_max3_f32 v144, v144, v70, v71
	v_max3_f32 v144, v144, v72, v73
	v_max3_f32 v144, v144, v74, v75
	v_max3_f32 v144, v144, v76, v77
	v_mfma_f32_32x32x16_bf16 v[16:31], v[194:197], v[206:209], v[16:31]
	v_max3_f32 v144, v144, v78, v79
	v_mov_b32_e32 v145, v144
	s_nop 1
	v_permlane32_swap_b32_e32 v144, v145
	v_max_f32_e32 v144, v144, v145
	v_sub_f32_e32 v145, v144, v174
	v_cmp_ge_f32_e32 vcc, s1, v145
	v_max_f32_e32 v145, v174, v144
	v_mfma_f32_32x32x16_bf16 v[16:31], v[198:201], v[210:213], v[16:31]
	v_sub_f32_e32 v144, v174, v145
	v_mul_f32_e32 v144, 0x3e0293ee, v144
	v_exp_f32_e32 v144, v144
	s_cmp_eq_u64 vcc, exec
	s_cselect_b64 s[8:9], -1, 0
	s_barrier
; #define SBAR() __builtin_amdgcn_sched_barrier(0)
; #define SWAIT() do { if constexpr (SDEPTH == 2) { if constexpr (DK == 192) asm volatile("s_waitcnt vmcnt(5)" ::: "memory"); else asm volatile("s_waitcnt vmcnt(4)" ::: "memory"); } else asm volatile("s_waitcnt vmcnt(0)" ::: "memory"); } while (0)
; #define RESC(a) do { if (__any((a) < 1.f)) { if (hi == 0) al_l[r32] = (a); asm volatile("s_waitcnt lgkmcnt(0)" ::: "memory"); \
;     _Pragma("unroll") for (int d = 0; d < 4; ++d) _Pragma("unroll") for (int r = 0; r < 16; ++r) o[d][r] *= al_l[crow(r, hi)]; } } while (0)
; template <int DK, int LDQ, int LDK, int LDV, int LDO, int SDEPTH, int NPARK>
; __device__ __forceinline__ void body(const bf16_t* __restrict__ Qb, const bf16_t* __restrict__ Kh, const bf16_t* __restrict__ Vh, bf16_t* __restrict__ Ob, int seq, char* lds, int tid, int wid) {
;     ...
;   f32x16 pA0, pA1, pB0, pB1; float mnA, mnB, alA, alB; bf16x8 pa0, pa1, pa2, pa3; const int NT = seq / KVBLK;
;   constexpr int SE = 0, SO = SDEPTH - 1;
;   SLOAD(SE, 0); asm volatile("s_waitcnt vmcnt(0)" ::: "memory"); SWRITE(0, SE); __syncthreads();
;   qkt<DK, NPARK>(pA0, pA1, K_lds, qr, qpark, r32, hi); partialSM<DK>(pA0, pA1, m_reg, mnA, alA);
;   SLOAD(SO, KVBLK); if constexpr (SDEPTH == 2) { if (2 < NT) SLOAD(SE, 2 * KVBLK); }
;   SWAIT(); SWRITE(1, SO); __syncthreads();
;   for (int j = 1; j + 1 < NT; j += 2) {
;     SBAR(); qkt<DK, NPARK>(pB0, pB1, K_lds + SHM_K, qr, qpark, r32, hi);
;     finishSM(pA0, pA1, alA, l_reg, pa0, pa1, pa2, pa3); SBAR();
;     SLOAD(SO, (j + SDEPTH) * KVBLK); SBAR();
;     pv_d0(o, vb0, pa0, pa1, pa2, pa3); partialSM<DK>(pB0, pB1, m_reg, mnB, alB);
;     __syncthreads(); SWAIT(); SWRITE(0, SE);
;     RESC(alB); __syncthreads();
;     SBAR(); qkt<DK, NPARK>(pA0, pA1, K_lds, qr, qpark, r32, hi);
;     finishSM(pB0, pB1, alB, l_reg, pa0, pa1, pa2, pa3); SBAR();
;     if (SDEPTH == 1 || j + 3 < NT) SLOAD(SE, (j + 1 + SDEPTH) * KVBLK); SBAR();
;     pv_d0(o, vb0 + (int)SHM_V, pa0, pa1, pa2, pa3); partialSM<DK>(pA0, pA1, m_reg, mnA, alA);
;     __syncthreads(); SWAIT(); SWRITE(1, SO);
;     RESC(alA); __syncthreads();
	s_waitcnt vmcnt(0)
	v_cndmask_b32_e64 v144, v144, 1.0, s[8:9]
	v_cmp_gt_f32_e32 vcc, 1.0, v144
	ds_write_b128 v164, v[128:131] offset:16384
	ds_write_b128 v165, v[132:135] offset:16384
	ds_write_b128 v162, v[136:139] offset:49152
	ds_write_b128 v163, v[140:143] offset:49152
	s_cbranch_vccz .LBB0_932
	s_and_saveexec_b64 s[12:13], s[6:7]
	ds_write_b32 v151, v144 offset:128
	s_or_b64 exec, exec, s[12:13]
	s_waitcnt lgkmcnt(0)
	v_add_u32_e32 v140, s95, v150
	ds_read_b128 v[128:131], v140 offset:224
	ds_read_b128 v[132:135], v140 offset:192
	ds_read_b128 v[136:139], v140 offset:160
	ds_read_b128 v[140:143], v140 offset:128
	s_waitcnt lgkmcnt(3)
	v_pk_mul_f32 v[12:13], v[12:13], v[128:129]
	s_waitcnt lgkmcnt(2)
	v_pk_mul_f32 v[8:9], v[8:9], v[132:133]
	s_waitcnt lgkmcnt(1)
	v_pk_mul_f32 v[4:5], v[4:5], v[136:137]
	v_pk_mul_f32 v[14:15], v[14:15], v[130:131]
	v_pk_mul_f32 v[10:11], v[10:11], v[134:135]
	v_pk_mul_f32 v[6:7], v[6:7], v[138:139]
	s_waitcnt lgkmcnt(0)
	v_pk_mul_f32 v[2:3], v[2:3], v[142:143]
	v_pk_mul_f32 v[0:1], v[0:1], v[140:141]
	v_pk_mul_f32 v[60:61], v[60:61], v[128:129]
	v_pk_mul_f32 v[56:57], v[56:57], v[132:133]
	v_pk_mul_f32 v[52:53], v[52:53], v[136:137]
	v_pk_mul_f32 v[62:63], v[62:63], v[130:131]
	v_pk_mul_f32 v[58:59], v[58:59], v[134:135]
	v_pk_mul_f32 v[54:55], v[54:55], v[138:139]
	v_pk_mul_f32 v[50:51], v[50:51], v[142:143]
	v_pk_mul_f32 v[48:49], v[48:49], v[140:141]
	v_pk_mul_f32 v[44:45], v[44:45], v[128:129]
	v_pk_mul_f32 v[40:41], v[40:41], v[132:133]
	v_pk_mul_f32 v[36:37], v[36:37], v[136:137]
	v_pk_mul_f32 v[46:47], v[46:47], v[130:131]
	v_pk_mul_f32 v[42:43], v[42:43], v[134:135]
	v_pk_mul_f32 v[38:39], v[38:39], v[138:139]
	v_pk_mul_f32 v[34:35], v[34:35], v[142:143]
	v_pk_mul_f32 v[32:33], v[32:33], v[140:141]
	v_pk_mul_f32 v[28:29], v[28:29], v[128:129]
	v_pk_mul_f32 v[24:25], v[24:25], v[132:133]
	v_pk_mul_f32 v[20:21], v[20:21], v[136:137]
	v_pk_mul_f32 v[30:31], v[30:31], v[130:131]
	v_pk_mul_f32 v[26:27], v[26:27], v[134:135]
	v_pk_mul_f32 v[22:23], v[22:23], v[138:139]
	v_pk_mul_f32 v[18:19], v[18:19], v[142:143]
	v_pk_mul_f32 v[16:17], v[16:17], v[140:141]
